# v29 + SwiGLU epilogue regenerated: g*u*rcp(i+e*i) with per-row constants (4 plain + 2 transcendental VALU per element instead of 6 + 2), 4 interleaved chains
# speedup vs baseline: 1.0123x; 1.0027x over previous
; __device__ __forceinline__ unsigned cvt_pk_bf16(float lo, float hi) { return __builtin_bit_cast(unsigned, __builtin_convertvector((f32x2_t){lo, hi}, bf16x2_t)); }
; __device__ __forceinline__ float silu_f(float x) { return x * sigmoid_f(x); }
;     __device__ __forceinline__ void operator()(const f32x4 (&acc)[2][2][4][2], const Unit& u, int wr, int wc, int fr, int fq, PG8_LAS unsigned char* lds, int parity) const {
;         float rs[8]; rs_load(rs, lds, parity, wr, fr);
;         const int row0 = u.pm * BM + wr * 64 + fr, col0 = u.pn * HALF + wc * 32 + 8 * fq;
; #pragma unroll
;         for (int ai = 0; ai < 2; ++ai)
; #pragma unroll
;             for (int m = 0; m < 4; ++m) { bf16_t* rowp = T + (size_t)(row0 + ai * HALF + m * 16) * ldt + col0; const float s = rs[ai * 4 + m];
;                 float o[8];
; #pragma unroll
;                 for (int n = 0; n < 2; ++n)
; #pragma unroll
;                     for (int j = 0; j < 4; ++j) { const float g = acc[ai][0][m][n][j] * s, uu = acc[ai][1][m][n][j] * s; o[n * 4 + j] = silu_f(g) * uu; }
;                 u32x4 w; w.x = cvt_pk_bf16(o[0], o[1]); w.y = cvt_pk_bf16(o[2], o[3]); w.z = cvt_pk_bf16(o[4], o[5]); w.w = cvt_pk_bf16(o[6], o[7]);
;                 *(u32x4*)rowp = w; }
.LBB0_648:
	v_lshl_add_u32 v144, v157, 10, v151
	ds_read_b32 v160, v144
	ds_read_b32 v156, v144 offset:64
	ds_read_b32 v154, v144 offset:128
	ds_read_b32 v152, v144 offset:192
	ds_read_b32 v150, v144 offset:512
	ds_read_b32 v148, v144 offset:576
	ds_read_b32 v146, v144 offset:640
	ds_read_b32 v142, v144 offset:704
	s_waitcnt lgkmcnt(0)
	v_lshl_add_u32 v158, s40, 8, v143
	v_lshl_add_u32 v162, s70, 7, v153
	v_mov_b64_e32 v[164:165], s[8:9]
	s_movk_i32 s13, 0x2c00
	v_lshlrev_b32_e32 v162, 1, v162
	v_mov_b32_e32 v163, 0
	v_mad_i64_i32 v[164:165], s[42:43], v158, s13, v[164:165]
	v_lshl_add_u64 v[164:165], v[164:165], 0, v[162:163]
	v_mul_f32_e32 v144, 0xbfb8aa3b, v160
	v_mul_f32_e32 v145, v160, v160
	v_rcp_f32_e32 v145, v145
	v_mul_f32_e32 v158, v126, v144
	v_mul_f32_e32 v159, v127, v144
	v_mul_f32_e32 v162, v128, v144
	v_mul_f32_e32 v163, v129, v144
	v_exp_f32_e32 v158, v158
	v_exp_f32_e32 v159, v159
	v_exp_f32_e32 v162, v162
	v_exp_f32_e32 v163, v163
	v_mul_f32_e32 v122, v126, v122
	v_mul_f32_e32 v123, v127, v123
	v_mul_f32_e32 v124, v128, v124
	v_mul_f32_e32 v125, v129, v125
	v_fma_f32 v158, v158, v145, v145
	v_fma_f32 v159, v159, v145, v145
	v_fma_f32 v162, v162, v145, v145
	v_fma_f32 v163, v163, v145, v145
	v_rcp_f32_e32 v158, v158
	v_rcp_f32_e32 v159, v159
	v_rcp_f32_e32 v162, v162
	v_rcp_f32_e32 v163, v163
	s_nop 0
	v_mul_f32_e32 v122, v122, v158
	v_mul_f32_e32 v123, v123, v159
	v_mul_f32_e32 v124, v124, v162
	v_mul_f32_e32 v125, v125, v163
	v_mul_f32_e32 v158, v118, v144
	v_mul_f32_e32 v159, v119, v144
	v_mul_f32_e32 v162, v120, v144
	v_mul_f32_e32 v163, v121, v144
	v_exp_f32_e32 v158, v158
	v_exp_f32_e32 v159, v159
	v_exp_f32_e32 v162, v162
	v_exp_f32_e32 v163, v163
	v_mul_f32_e32 v114, v118, v114
	v_mul_f32_e32 v115, v119, v115
	v_mul_f32_e32 v116, v120, v116
	v_mul_f32_e32 v117, v121, v117
	v_fma_f32 v158, v158, v145, v145
	v_fma_f32 v159, v159, v145, v145
	v_fma_f32 v162, v162, v145, v145
	v_fma_f32 v163, v163, v145, v145
	v_rcp_f32_e32 v158, v158
	v_rcp_f32_e32 v159, v159
	v_rcp_f32_e32 v162, v162
	v_rcp_f32_e32 v163, v163
	s_nop 0
	v_mul_f32_e32 v114, v114, v158
	v_mul_f32_e32 v115, v115, v159
	v_mul_f32_e32 v116, v116, v162
	v_mul_f32_e32 v117, v117, v163
	v_cvt_pk_bf16_f32 v126, v122, v123
	v_cvt_pk_bf16_f32 v127, v124, v125
	v_cvt_pk_bf16_f32 v128, v114, v115
	v_cvt_pk_bf16_f32 v129, v116, v117
	global_store_dwordx4 v[164:165], v[126:129], off
	v_mul_f32_e32 v144, 0xbfb8aa3b, v156
	v_mul_f32_e32 v145, v156, v156
	v_rcp_f32_e32 v145, v145
	v_mul_f32_e32 v158, v110, v144
	v_mul_f32_e32 v159, v111, v144
	v_mul_f32_e32 v162, v112, v144
	v_mul_f32_e32 v163, v113, v144
	v_exp_f32_e32 v158, v158
	v_exp_f32_e32 v159, v159
	v_exp_f32_e32 v162, v162
	v_exp_f32_e32 v163, v163
	v_mul_f32_e32 v106, v110, v106
	v_mul_f32_e32 v107, v111, v107
	v_mul_f32_e32 v108, v112, v108
	v_mul_f32_e32 v109, v113, v109
	v_fma_f32 v158, v158, v145, v145
	v_fma_f32 v159, v159, v145, v145
	v_fma_f32 v162, v162, v145, v145
	v_fma_f32 v163, v163, v145, v145
	v_rcp_f32_e32 v158, v158
	v_rcp_f32_e32 v159, v159
	v_rcp_f32_e32 v162, v162
	v_rcp_f32_e32 v163, v163
	s_nop 0
	v_mul_f32_e32 v106, v106, v158
	v_mul_f32_e32 v107, v107, v159
	v_mul_f32_e32 v108, v108, v162
	v_mul_f32_e32 v109, v109, v163
	v_mul_f32_e32 v158, v102, v144
	v_mul_f32_e32 v159, v103, v144
	v_mul_f32_e32 v162, v104, v144
	v_mul_f32_e32 v163, v105, v144
	v_exp_f32_e32 v158, v158
	v_exp_f32_e32 v159, v159
	v_exp_f32_e32 v162, v162
	v_exp_f32_e32 v163, v163
	v_mul_f32_e32 v98, v102, v98
	v_mul_f32_e32 v99, v103, v99
	v_mul_f32_e32 v100, v104, v100
	v_mul_f32_e32 v101, v105, v101
	v_fma_f32 v158, v158, v145, v145
	v_fma_f32 v159, v159, v145, v145
	v_fma_f32 v162, v162, v145, v145
	v_fma_f32 v163, v163, v145, v145
	v_rcp_f32_e32 v158, v158
	v_rcp_f32_e32 v159, v159
	v_rcp_f32_e32 v162, v162
	v_rcp_f32_e32 v163, v163
	s_mov_b64 s[42:43], 180224
	v_lshl_add_u64 v[166:167], v[164:165], 0, s[42:43]
	v_mul_f32_e32 v98, v98, v158
	v_mul_f32_e32 v99, v99, v159
	v_mul_f32_e32 v100, v100, v162
	v_mul_f32_e32 v101, v101, v163
	v_cvt_pk_bf16_f32 v110, v106, v107
	v_cvt_pk_bf16_f32 v111, v108, v109
	v_cvt_pk_bf16_f32 v112, v98, v99
	v_cvt_pk_bf16_f32 v113, v100, v101
	global_store_dwordx4 v[166:167], v[110:113], off
	v_mul_f32_e32 v144, 0xbfb8aa3b, v154
	v_mul_f32_e32 v145, v154, v154
	v_rcp_f32_e32 v145, v145
	v_mul_f32_e32 v158, v94, v144
	v_mul_f32_e32 v159, v95, v144
	v_mul_f32_e32 v162, v96, v144
	v_mul_f32_e32 v163, v97, v144
	v_exp_f32_e32 v158, v158
	v_exp_f32_e32 v159, v159
	v_exp_f32_e32 v162, v162
	v_exp_f32_e32 v163, v163
	v_mul_f32_e32 v90, v94, v90
	v_mul_f32_e32 v91, v95, v91
	v_mul_f32_e32 v92, v96, v92
	v_mul_f32_e32 v93, v97, v93
	v_fma_f32 v158, v158, v145, v145
	v_fma_f32 v159, v159, v145, v145
	v_fma_f32 v162, v162, v145, v145
	v_fma_f32 v163, v163, v145, v145
	v_rcp_f32_e32 v158, v158
	v_rcp_f32_e32 v159, v159
	v_rcp_f32_e32 v162, v162
	v_rcp_f32_e32 v163, v163
	s_nop 0
	v_mul_f32_e32 v90, v90, v158
	v_mul_f32_e32 v91, v91, v159
	v_mul_f32_e32 v92, v92, v162
	v_mul_f32_e32 v93, v93, v163
	v_mul_f32_e32 v158, v86, v144
	v_mul_f32_e32 v159, v87, v144
	v_mul_f32_e32 v162, v88, v144
	v_mul_f32_e32 v163, v89, v144
	v_exp_f32_e32 v158, v158
	v_exp_f32_e32 v159, v159
	v_exp_f32_e32 v162, v162
	v_exp_f32_e32 v163, v163
	v_mul_f32_e32 v82, v86, v82
	v_mul_f32_e32 v83, v87, v83
	v_mul_f32_e32 v84, v88, v84
	v_mul_f32_e32 v85, v89, v85
	v_fma_f32 v158, v158, v145, v145
	v_fma_f32 v159, v159, v145, v145
	v_fma_f32 v162, v162, v145, v145
	v_fma_f32 v163, v163, v145, v145
	v_rcp_f32_e32 v158, v158
	v_rcp_f32_e32 v159, v159
	v_rcp_f32_e32 v162, v162
	v_rcp_f32_e32 v163, v163
	s_mov_b64 s[42:43], 360448
; __device__ __forceinline__ unsigned cvt_pk_bf16(float lo, float hi) { return __builtin_bit_cast(unsigned, __builtin_convertvector((f32x2_t){lo, hi}, bf16x2_t)); }
; __device__ __forceinline__ float silu_f(float x) { return x * sigmoid_f(x); }
;     __device__ __forceinline__ void operator()(const f32x4 (&acc)[2][2][4][2], const Unit& u, int wr, int wc, int fr, int fq, PG8_LAS unsigned char* lds, int parity) const {
;     ...
;         for (int ai = 0; ai < 2; ++ai)
; #pragma unroll
;             for (int m = 0; m < 4; ++m) { bf16_t* rowp = T + (size_t)(row0 + ai * HALF + m * 16) * ldt + col0; const float s = rs[ai * 4 + m];
;                 float o[8];
; #pragma unroll
;                 for (int n = 0; n < 2; ++n)
; #pragma unroll
;                     for (int j = 0; j < 4; ++j) { const float g = acc[ai][0][m][n][j] * s, uu = acc[ai][1][m][n][j] * s; o[n * 4 + j] = silu_f(g) * uu; }
;                 u32x4 w; w.x = cvt_pk_bf16(o[0], o[1]); w.y = cvt_pk_bf16(o[2], o[3]); w.z = cvt_pk_bf16(o[4], o[5]); w.w = cvt_pk_bf16(o[6], o[7]);
;                 *(u32x4*)rowp = w; }
	v_lshl_add_u64 v[166:167], v[164:165], 0, s[42:43]
	v_mul_f32_e32 v82, v82, v158
	v_mul_f32_e32 v83, v83, v159
	v_mul_f32_e32 v84, v84, v162
	v_mul_f32_e32 v85, v85, v163
	v_cvt_pk_bf16_f32 v94, v90, v91
	v_cvt_pk_bf16_f32 v95, v92, v93
	v_cvt_pk_bf16_f32 v96, v82, v83
	v_cvt_pk_bf16_f32 v97, v84, v85
	global_store_dwordx4 v[166:167], v[94:97], off
	v_mul_f32_e32 v144, 0xbfb8aa3b, v152
	v_mul_f32_e32 v145, v152, v152
	v_rcp_f32_e32 v145, v145
	v_mul_f32_e32 v158, v78, v144
	v_mul_f32_e32 v159, v79, v144
	v_mul_f32_e32 v162, v80, v144
	v_mul_f32_e32 v163, v81, v144
	v_exp_f32_e32 v158, v158
	v_exp_f32_e32 v159, v159
	v_exp_f32_e32 v162, v162
	v_exp_f32_e32 v163, v163
	v_mul_f32_e32 v74, v78, v74
	v_mul_f32_e32 v75, v79, v75
	v_mul_f32_e32 v76, v80, v76
	v_mul_f32_e32 v77, v81, v77
	v_fma_f32 v158, v158, v145, v145
	v_fma_f32 v159, v159, v145, v145
	v_fma_f32 v162, v162, v145, v145
	v_fma_f32 v163, v163, v145, v145
	v_rcp_f32_e32 v158, v158
	v_rcp_f32_e32 v159, v159
	v_rcp_f32_e32 v162, v162
	v_rcp_f32_e32 v163, v163
	s_nop 0
	v_mul_f32_e32 v74, v74, v158
	v_mul_f32_e32 v75, v75, v159
	v_mul_f32_e32 v76, v76, v162
	v_mul_f32_e32 v77, v77, v163
	v_mul_f32_e32 v158, v70, v144
	v_mul_f32_e32 v159, v71, v144
	v_mul_f32_e32 v162, v72, v144
	v_mul_f32_e32 v163, v73, v144
	v_exp_f32_e32 v158, v158
	v_exp_f32_e32 v159, v159
	v_exp_f32_e32 v162, v162
	v_exp_f32_e32 v163, v163
	v_mul_f32_e32 v66, v70, v66
	v_mul_f32_e32 v67, v71, v67
	v_mul_f32_e32 v68, v72, v68
	v_mul_f32_e32 v69, v73, v69
	v_fma_f32 v158, v158, v145, v145
	v_fma_f32 v159, v159, v145, v145
	v_fma_f32 v162, v162, v145, v145
	v_fma_f32 v163, v163, v145, v145
	v_rcp_f32_e32 v158, v158
	v_rcp_f32_e32 v159, v159
	v_rcp_f32_e32 v162, v162
	v_rcp_f32_e32 v163, v163
	s_mov_b64 s[42:43], 540672
	v_lshl_add_u64 v[166:167], v[164:165], 0, s[42:43]
	v_mul_f32_e32 v66, v66, v158
	v_mul_f32_e32 v67, v67, v159
	v_mul_f32_e32 v68, v68, v162
	v_mul_f32_e32 v69, v69, v163
	v_cvt_pk_bf16_f32 v78, v74, v75
	v_cvt_pk_bf16_f32 v79, v76, v77
	v_cvt_pk_bf16_f32 v80, v66, v67
	v_cvt_pk_bf16_f32 v81, v68, v69
	global_store_dwordx4 v[166:167], v[78:81], off
	v_mul_f32_e32 v144, 0xbfb8aa3b, v150
	v_mul_f32_e32 v145, v150, v150
	v_rcp_f32_e32 v145, v145
	v_mul_f32_e32 v158, v62, v144
	v_mul_f32_e32 v159, v63, v144
	v_mul_f32_e32 v162, v64, v144
	v_mul_f32_e32 v163, v65, v144
	v_exp_f32_e32 v158, v158
	v_exp_f32_e32 v159, v159
	v_exp_f32_e32 v162, v162
	v_exp_f32_e32 v163, v163
	v_mul_f32_e32 v58, v62, v58
	v_mul_f32_e32 v59, v63, v59
	v_mul_f32_e32 v60, v64, v60
	v_mul_f32_e32 v61, v65, v61
	v_fma_f32 v158, v158, v145, v145
	v_fma_f32 v159, v159, v145, v145
	v_fma_f32 v162, v162, v145, v145
	v_fma_f32 v163, v163, v145, v145
	v_rcp_f32_e32 v158, v158
	v_rcp_f32_e32 v159, v159
	v_rcp_f32_e32 v162, v162
	v_rcp_f32_e32 v163, v163
	s_nop 0
	v_mul_f32_e32 v58, v58, v158
	v_mul_f32_e32 v59, v59, v159
	v_mul_f32_e32 v60, v60, v162
	v_mul_f32_e32 v61, v61, v163
	v_mul_f32_e32 v158, v54, v144
	v_mul_f32_e32 v159, v55, v144
	v_mul_f32_e32 v162, v56, v144
	v_mul_f32_e32 v163, v57, v144
	v_exp_f32_e32 v158, v158
	v_exp_f32_e32 v159, v159
	v_exp_f32_e32 v162, v162
	v_exp_f32_e32 v163, v163
	v_mul_f32_e32 v50, v54, v50
	v_mul_f32_e32 v51, v55, v51
	v_mul_f32_e32 v52, v56, v52
	v_mul_f32_e32 v53, v57, v53
	v_fma_f32 v158, v158, v145, v145
	v_fma_f32 v159, v159, v145, v145
	v_fma_f32 v162, v162, v145, v145
	v_fma_f32 v163, v163, v145, v145
	v_rcp_f32_e32 v158, v158
	v_rcp_f32_e32 v159, v159
	v_rcp_f32_e32 v162, v162
	v_rcp_f32_e32 v163, v163
	s_mov_b64 s[42:43], 1441792
	v_lshl_add_u64 v[166:167], v[164:165], 0, s[42:43]
	v_mul_f32_e32 v50, v50, v158
	v_mul_f32_e32 v51, v51, v159
	v_mul_f32_e32 v52, v52, v162
	v_mul_f32_e32 v53, v53, v163
	v_cvt_pk_bf16_f32 v62, v58, v59
	v_cvt_pk_bf16_f32 v63, v60, v61
	v_cvt_pk_bf16_f32 v64, v50, v51
	v_cvt_pk_bf16_f32 v65, v52, v53
	global_store_dwordx4 v[166:167], v[62:65], off
	v_mul_f32_e32 v144, 0xbfb8aa3b, v148
	v_mul_f32_e32 v145, v148, v148
	v_rcp_f32_e32 v145, v145
	v_mul_f32_e32 v158, v46, v144
	v_mul_f32_e32 v159, v47, v144
	v_mul_f32_e32 v162, v48, v144
	v_mul_f32_e32 v163, v49, v144
	v_exp_f32_e32 v158, v158
	v_exp_f32_e32 v159, v159
	v_exp_f32_e32 v162, v162
	v_exp_f32_e32 v163, v163
	v_mul_f32_e32 v42, v46, v42
	v_mul_f32_e32 v43, v47, v43
	v_mul_f32_e32 v44, v48, v44
	v_mul_f32_e32 v45, v49, v45
	v_fma_f32 v158, v158, v145, v145
	v_fma_f32 v159, v159, v145, v145
	v_fma_f32 v162, v162, v145, v145
	v_fma_f32 v163, v163, v145, v145
	v_rcp_f32_e32 v158, v158
	v_rcp_f32_e32 v159, v159
	v_rcp_f32_e32 v162, v162
	v_rcp_f32_e32 v163, v163
	s_nop 0
	v_mul_f32_e32 v42, v42, v158
	v_mul_f32_e32 v43, v43, v159
	v_mul_f32_e32 v44, v44, v162
; __device__ __forceinline__ unsigned cvt_pk_bf16(float lo, float hi) { return __builtin_bit_cast(unsigned, __builtin_convertvector((f32x2_t){lo, hi}, bf16x2_t)); }
; __device__ __forceinline__ float silu_f(float x) { return x * sigmoid_f(x); }
; #define PG8_BAR __builtin_amdgcn_s_barrier()
;     __device__ __forceinline__ void operator()(const f32x4 (&acc)[2][2][4][2], const Unit& u, int wr, int wc, int fr, int fq, PG8_LAS unsigned char* lds, int parity) const {
;     ...
;         for (int ai = 0; ai < 2; ++ai)
; #pragma unroll
;             for (int m = 0; m < 4; ++m) { bf16_t* rowp = T + (size_t)(row0 + ai * HALF + m * 16) * ldt + col0; const float s = rs[ai * 4 + m];
;                 float o[8];
; #pragma unroll
;                 for (int n = 0; n < 2; ++n)
; #pragma unroll
;                     for (int j = 0; j < 4; ++j) { const float g = acc[ai][0][m][n][j] * s, uu = acc[ai][1][m][n][j] * s; o[n * 4 + j] = silu_f(g) * uu; }
;                 u32x4 w; w.x = cvt_pk_bf16(o[0], o[1]); w.y = cvt_pk_bf16(o[2], o[3]); w.z = cvt_pk_bf16(o[4], o[5]); w.w = cvt_pk_bf16(o[6], o[7]);
;                 *(u32x4*)rowp = w; }
; template <class Epi, class Sched, bool ALIGN_EPI = false, bool SP2 = false>
; __device__ __forceinline__ void gemm_phase(PG8_LAS unsigned char* lds, const Gemm g, const Sched& S, const Epi& E, const int wave_id) {
;     ...
;         E(acc, cur, wr, wc, fr, fq, lds, tp); S.done(cur);
;         if (!has_next) break;
;         if (newpanel) tp ^= 1;
; #pragma unroll
;         for (int a = 0; a < 2; ++a)
; #pragma unroll
;             for (int b = 0; b < 2; ++b)
; #pragma unroll
;                 for (int m = 0; m < 4; ++m)
; #pragma unroll
;                     for (int n = 0; n < 2; ++n) acc[a][b][m][n] = (f32x4){0.f, 0.f, 0.f, 0.f};
;         cur = nxt; cA = nA; cB = nB; ++ui;
;         if constexpr (ALIGN_EPI) { if (wr == 1) PG8_BAR; }
	v_mul_f32_e32 v45, v45, v163
	v_mul_f32_e32 v158, v38, v144
	v_mul_f32_e32 v159, v39, v144
	v_mul_f32_e32 v162, v40, v144
	v_mul_f32_e32 v163, v41, v144
	v_exp_f32_e32 v158, v158
	v_exp_f32_e32 v159, v159
	v_exp_f32_e32 v162, v162
	v_exp_f32_e32 v163, v163
	v_mul_f32_e32 v34, v38, v34
	v_mul_f32_e32 v35, v39, v35
	v_mul_f32_e32 v36, v40, v36
	v_mul_f32_e32 v37, v41, v37
	v_fma_f32 v158, v158, v145, v145
	v_fma_f32 v159, v159, v145, v145
	v_fma_f32 v162, v162, v145, v145
	v_fma_f32 v163, v163, v145, v145
	v_rcp_f32_e32 v158, v158
	v_rcp_f32_e32 v159, v159
	v_rcp_f32_e32 v162, v162
	v_rcp_f32_e32 v163, v163
	s_mov_b64 s[42:43], 1622016
	v_lshl_add_u64 v[166:167], v[164:165], 0, s[42:43]
	v_mul_f32_e32 v34, v34, v158
	v_mul_f32_e32 v35, v35, v159
	v_mul_f32_e32 v36, v36, v162
	v_mul_f32_e32 v37, v37, v163
	v_cvt_pk_bf16_f32 v46, v42, v43
	v_cvt_pk_bf16_f32 v47, v44, v45
	v_cvt_pk_bf16_f32 v48, v34, v35
	v_cvt_pk_bf16_f32 v49, v36, v37
	global_store_dwordx4 v[166:167], v[46:49], off
	v_mul_f32_e32 v144, 0xbfb8aa3b, v146
	v_mul_f32_e32 v145, v146, v146
	v_rcp_f32_e32 v145, v145
	v_mul_f32_e32 v158, v30, v144
	v_mul_f32_e32 v159, v31, v144
	v_mul_f32_e32 v162, v32, v144
	v_mul_f32_e32 v163, v33, v144
	v_exp_f32_e32 v158, v158
	v_exp_f32_e32 v159, v159
	v_exp_f32_e32 v162, v162
	v_exp_f32_e32 v163, v163
	v_mul_f32_e32 v26, v30, v26
	v_mul_f32_e32 v27, v31, v27
	v_mul_f32_e32 v28, v32, v28
	v_mul_f32_e32 v29, v33, v29
	v_fma_f32 v158, v158, v145, v145
	v_fma_f32 v159, v159, v145, v145
	v_fma_f32 v162, v162, v145, v145
	v_fma_f32 v163, v163, v145, v145
	v_rcp_f32_e32 v158, v158
	v_rcp_f32_e32 v159, v159
	v_rcp_f32_e32 v162, v162
	v_rcp_f32_e32 v163, v163
	s_nop 0
	v_mul_f32_e32 v26, v26, v158
	v_mul_f32_e32 v27, v27, v159
	v_mul_f32_e32 v28, v28, v162
	v_mul_f32_e32 v29, v29, v163
	v_mul_f32_e32 v158, v22, v144
	v_mul_f32_e32 v159, v23, v144
	v_mul_f32_e32 v162, v24, v144
	v_mul_f32_e32 v163, v25, v144
	v_exp_f32_e32 v158, v158
	v_exp_f32_e32 v159, v159
	v_exp_f32_e32 v162, v162
	v_exp_f32_e32 v163, v163
	v_mul_f32_e32 v18, v22, v18
	v_mul_f32_e32 v19, v23, v19
	v_mul_f32_e32 v20, v24, v20
	v_mul_f32_e32 v21, v25, v21
	v_fma_f32 v158, v158, v145, v145
	v_fma_f32 v159, v159, v145, v145
	v_fma_f32 v162, v162, v145, v145
	v_fma_f32 v163, v163, v145, v145
	v_rcp_f32_e32 v158, v158
	v_rcp_f32_e32 v159, v159
	v_rcp_f32_e32 v162, v162
	v_rcp_f32_e32 v163, v163
	s_mov_b64 s[42:43], 1802240
	v_lshl_add_u64 v[166:167], v[164:165], 0, s[42:43]
	v_mul_f32_e32 v18, v18, v158
	v_mul_f32_e32 v19, v19, v159
	v_mul_f32_e32 v20, v20, v162
	v_mul_f32_e32 v21, v21, v163
	v_cvt_pk_bf16_f32 v30, v26, v27
	v_cvt_pk_bf16_f32 v31, v28, v29
	v_cvt_pk_bf16_f32 v32, v18, v19
	v_cvt_pk_bf16_f32 v33, v20, v21
	global_store_dwordx4 v[166:167], v[30:33], off
	v_mul_f32_e32 v144, 0xbfb8aa3b, v142
	v_mul_f32_e32 v145, v142, v142
	v_rcp_f32_e32 v145, v145
	v_mul_f32_e32 v158, v14, v144
	v_mul_f32_e32 v159, v15, v144
	v_mul_f32_e32 v162, v16, v144
	v_mul_f32_e32 v163, v17, v144
	v_exp_f32_e32 v158, v158
	v_exp_f32_e32 v159, v159
	v_exp_f32_e32 v162, v162
	v_exp_f32_e32 v163, v163
	v_mul_f32_e32 v10, v14, v10
	v_mul_f32_e32 v11, v15, v11
	v_mul_f32_e32 v12, v16, v12
	v_mul_f32_e32 v13, v17, v13
	v_fma_f32 v158, v158, v145, v145
	v_fma_f32 v159, v159, v145, v145
	v_fma_f32 v162, v162, v145, v145
	v_fma_f32 v163, v163, v145, v145
	v_rcp_f32_e32 v158, v158
	v_rcp_f32_e32 v159, v159
	v_rcp_f32_e32 v162, v162
	v_rcp_f32_e32 v163, v163
	s_nop 0
	v_mul_f32_e32 v10, v10, v158
	v_mul_f32_e32 v11, v11, v159
	v_mul_f32_e32 v12, v12, v162
	v_mul_f32_e32 v13, v13, v163
	v_mul_f32_e32 v158, v6, v144
	v_mul_f32_e32 v159, v7, v144
	v_mul_f32_e32 v162, v8, v144
	v_mul_f32_e32 v163, v9, v144
	v_exp_f32_e32 v158, v158
	v_exp_f32_e32 v159, v159
	v_exp_f32_e32 v162, v162
	v_exp_f32_e32 v163, v163
	v_mul_f32_e32 v2, v6, v2
	v_mul_f32_e32 v3, v7, v3
	v_mul_f32_e32 v4, v8, v4
	v_mul_f32_e32 v5, v9, v5
	v_fma_f32 v158, v158, v145, v145
	v_fma_f32 v159, v159, v145, v145
	v_fma_f32 v162, v162, v145, v145
	v_fma_f32 v163, v163, v145, v145
	v_rcp_f32_e32 v158, v158
	v_rcp_f32_e32 v159, v159
	v_rcp_f32_e32 v162, v162
	v_rcp_f32_e32 v163, v163
	s_mov_b64 s[42:43], 1982464
	v_lshl_add_u64 v[166:167], v[164:165], 0, s[42:43]
	v_mul_f32_e32 v2, v2, v158
	v_mul_f32_e32 v3, v3, v159
	v_mul_f32_e32 v4, v4, v162
	v_mul_f32_e32 v5, v5, v163
	v_cvt_pk_bf16_f32 v14, v10, v11
	v_cvt_pk_bf16_f32 v15, v12, v13
	v_cvt_pk_bf16_f32 v16, v2, v3
	v_cvt_pk_bf16_f32 v17, v4, v5
	global_store_dwordx4 v[166:167], v[14:17], off
	s_andn2_b64 vcc, exec, s[38:39]
	s_cbranch_vccnz .LBB0_651
	s_andn2_b64 vcc, exec, s[4:5]
	s_cbranch_vccnz .LBB0_636
	s_barrier
	s_branch .LBB0_636
